# NA flash64 loop: s_setprio 1/0 around the S-MFMA and PV-MFMA groups (static priority raise), on top of mixers co-scheduling
# baseline (speedup 1.0000x reference)
.LBB0_250:
	s_and_saveexec_b64 s[58:59], s[10:11]
	s_cbranch_execz .LBB0_286
	v_cndmask_b32_e64 v60, -v219, 0, s[8:9]
	v_cndmask_b32_e64 v76, -v220, 0, s[8:9]
	v_lshl_add_u32 v0, s26, 14, v168
	ds_read_b128 v[64:67], v0
	ds_read_b128 v[68:71], v0 offset:4096
	ds_read_b128 v[72:75], v0 offset:1024
	ds_read_b128 v[80:83], v0 offset:5120
	ds_read_b128 v[84:87], v0 offset:2048
	ds_read_b128 v[88:91], v0 offset:6144
	ds_read_b128 v[92:95], v0 offset:3072
	ds_read_b128 v[96:99], v0 offset:7168
	v_mov_b32_e32 v61, v60
	v_mov_b32_e32 v62, v60
	v_mov_b32_e32 v63, v60
	v_mov_b32_e32 v77, v76
	v_mov_b32_e32 v78, v76
	v_mov_b32_e32 v79, v76
	s_waitcnt lgkmcnt(0)
	s_setprio 1
	v_mfma_f32_16x16x32_bf16 v[100:103], v[64:67], v[4:7], v[60:63]
	s_mov_b64 s[10:11], -1
	s_andn2_b64 vcc, exec, s[82:83]
	v_mfma_f32_16x16x32_bf16 v[64:67], v[64:67], v[12:15], v[76:79]
	v_mfma_f32_16x16x32_bf16 v[108:111], v[68:71], v[8:11], v[100:103]
	v_mfma_f32_16x16x32_bf16 v[68:71], v[68:71], v[16:19], v[64:67]
	v_mfma_f32_16x16x32_bf16 v[64:67], v[72:75], v[4:7], v[60:63]
	v_mfma_f32_16x16x32_bf16 v[72:75], v[72:75], v[12:15], v[76:79]
	v_mfma_f32_16x16x32_bf16 v[112:115], v[80:83], v[8:11], v[64:67]
	v_mfma_f32_16x16x32_bf16 v[72:75], v[80:83], v[16:19], v[72:75]
	v_mfma_f32_16x16x32_bf16 v[64:67], v[84:87], v[4:7], v[60:63]
	v_mfma_f32_16x16x32_bf16 v[80:83], v[84:87], v[12:15], v[76:79]
	v_mfma_f32_16x16x32_bf16 v[60:63], v[92:95], v[4:7], v[60:63]
	v_mfma_f32_16x16x32_bf16 v[76:79], v[92:95], v[12:15], v[76:79]
	v_mfma_f32_16x16x32_bf16 v[120:123], v[88:91], v[8:11], v[64:67]
	v_mfma_f32_16x16x32_bf16 v[64:67], v[88:91], v[16:19], v[80:83]
	v_mfma_f32_16x16x32_bf16 v[116:119], v[96:99], v[8:11], v[60:63]
	v_mfma_f32_16x16x32_bf16 v[60:63], v[96:99], v[16:19], v[76:79]
	s_setprio 0
	ds_read_b128 v[92:95], v0 offset:8192
	s_nop 2
	ds_read_b128 v[76:79], v0 offset:12288
	ds_read_b128 v[80:83], v0 offset:9216
	ds_read_b128 v[84:87], v0 offset:13312
	ds_read_b128 v[96:99], v0 offset:10240
	ds_read_b128 v[88:91], v0 offset:14336
	ds_read_b128 v[100:103], v0 offset:11264
	ds_read_b128 v[104:107], v0 offset:15360
	s_cbranch_vccnz .LBB0_253
	v_mov_b64_e32 v[132:133], v[62:63]
	v_mov_b64_e32 v[134:135], v[66:67]
	v_mov_b64_e32 v[142:143], v[118:119]
	v_mov_b64_e32 v[126:127], v[74:75]
	v_mov_b64_e32 v[136:137], v[114:115]
	v_mov_b64_e32 v[144:145], v[122:123]
	v_mov_b64_e32 v[128:129], v[70:71]
	v_mov_b64_e32 v[138:139], v[110:111]
	s_mov_b64 s[10:11], 0
	v_mov_b64_e32 v[130:131], v[60:61]
	v_mov_b64_e32 v[140:141], v[116:117]
	v_mov_b64_e32 v[132:133], v[64:65]
	v_mov_b64_e32 v[142:143], v[120:121]
	v_mov_b64_e32 v[124:125], v[72:73]
	v_mov_b64_e32 v[134:135], v[112:113]
	v_mov_b64_e32 v[126:127], v[68:69]
	v_mov_b64_e32 v[136:137], v[108:109]

.LBB0_285:
	s_or_b64 exec, exec, s[82:83]
	v_exp_f32_e32 v0, v108
	v_exp_f32_e32 v2, v109
	v_exp_f32_e32 v3, v110
	v_exp_f32_e32 v109, v111
	v_exp_f32_e32 v110, v112
	v_exp_f32_e32 v111, v113
	v_exp_f32_e32 v112, v114
	v_exp_f32_e32 v113, v115
	v_cvt_pk_bf16_f32 v108, v0, v2
	v_exp_f32_e32 v0, v120
	v_exp_f32_e32 v2, v121
	v_cvt_pk_bf16_f32 v110, v110, v111
	v_cvt_pk_bf16_f32 v111, v112, v113
	v_cvt_pk_bf16_f32 v109, v3, v109
	v_cvt_pk_bf16_f32 v112, v0, v2
	v_exp_f32_e32 v0, v68
	v_exp_f32_e32 v2, v69
	v_exp_f32_e32 v3, v122
	v_exp_f32_e32 v113, v123
	s_mov_b32 s81, s80
	v_cvt_pk_bf16_f32 v68, v0, v2
	v_exp_f32_e32 v0, v64
	v_exp_f32_e32 v2, v65
	v_exp_f32_e32 v65, v67
	s_mov_b32 s82, s80
	s_mov_b32 s83, s80
	v_cvt_pk_bf16_f32 v64, v0, v2
	v_exp_f32_e32 v0, v60
	v_exp_f32_e32 v2, v61
	v_exp_f32_e32 v60, v62
	v_exp_f32_e32 v61, v63
	v_cvt_pk_bf16_f32 v113, v3, v113
	v_exp_f32_e32 v3, v70
	v_exp_f32_e32 v69, v71
	v_cvt_pk_bf16_f32 v67, v60, v61
	v_mov_b64_e32 v[60:61], s[80:81]
	v_exp_f32_e32 v70, v72
	v_exp_f32_e32 v71, v73
	v_exp_f32_e32 v72, v74
	v_exp_f32_e32 v73, v75
	v_mov_b64_e32 v[62:63], s[82:83]
	v_exp_f32_e32 v114, v116
	v_exp_f32_e32 v115, v117
	v_exp_f32_e32 v116, v118
	v_exp_f32_e32 v117, v119
	v_cvt_pk_bf16_f32 v69, v3, v69
	v_cvt_pk_bf16_f32 v70, v70, v71
	v_cvt_pk_bf16_f32 v71, v72, v73
	v_exp_f32_e32 v3, v66
	s_waitcnt lgkmcnt(7)
	s_setprio 1
	v_mfma_f32_16x16x32_bf16 v[52:55], v[92:95], v[108:111], v[52:55]
	v_cvt_pk_bf16_f32 v114, v114, v115
	v_cvt_pk_bf16_f32 v115, v116, v117
	v_cvt_pk_bf16_f32 v65, v3, v65
	v_mfma_f32_16x16x32_bf16 v[32:35], v[92:95], v[68:71], v[32:35]
	v_cvt_pk_bf16_f32 v66, v0, v2
	s_andn2_b64 s[8:9], s[8:9], exec
	s_waitcnt lgkmcnt(5)
	v_mfma_f32_16x16x32_bf16 v[48:51], v[80:83], v[108:111], v[48:51]
	v_mfma_f32_16x16x32_bf16 v[28:31], v[80:83], v[68:71], v[28:31]
	s_waitcnt lgkmcnt(3)
	v_mfma_f32_16x16x32_bf16 v[44:47], v[96:99], v[108:111], v[44:47]
	v_mfma_f32_16x16x32_bf16 v[24:27], v[96:99], v[68:71], v[24:27]
	s_waitcnt lgkmcnt(1)
	v_mfma_f32_16x16x32_bf16 v[40:43], v[100:103], v[108:111], v[40:43]
	v_mfma_f32_16x16x32_bf16 v[20:23], v[100:103], v[68:71], v[20:23]
	v_mfma_f32_16x16x32_bf16 v[56:59], v[60:63], v[108:111], v[56:59]
	v_mfma_f32_16x16x32_bf16 v[36:39], v[60:63], v[68:71], v[36:39]
	v_mfma_f32_16x16x32_bf16 v[52:55], v[76:79], v[112:115], v[52:55]
	v_mfma_f32_16x16x32_bf16 v[32:35], v[76:79], v[64:67], v[32:35]
	v_mfma_f32_16x16x32_bf16 v[48:51], v[84:87], v[112:115], v[48:51]
	v_mfma_f32_16x16x32_bf16 v[28:31], v[84:87], v[64:67], v[28:31]
	v_mfma_f32_16x16x32_bf16 v[44:47], v[88:91], v[112:115], v[44:47]
	v_mfma_f32_16x16x32_bf16 v[24:27], v[88:91], v[64:67], v[24:27]
	s_waitcnt lgkmcnt(0)
	v_mfma_f32_16x16x32_bf16 v[40:43], v[104:107], v[112:115], v[40:43]
	v_mfma_f32_16x16x32_bf16 v[20:23], v[104:107], v[64:67], v[20:23]
	v_mfma_f32_16x16x32_bf16 v[56:59], v[60:63], v[112:115], v[56:59]
	v_mfma_f32_16x16x32_bf16 v[36:39], v[60:63], v[64:67], v[36:39]
	s_setprio 0
